# neighbourhood attention: per-wave tile order rotated so the 8 waves of a workgroup read the same K/V tile in the same step
# speedup vs baseline: 1.0161x; 1.0051x over previous
; template <int KIND, int QH>
; __device__ __forceinline__ void attn_unit(const AttnBufs& a, int u, int lane, const LAS float* rpbt, float bndA, float bndB) {
;     ...
;     if (KIND == 0) { r = u & 127; h = (u >> 7) & 7; b = u >> 10; qrow0 = b * SEQ + r * 64 + 32 * QH; head16 = h; hv = h; bound = bndA;
;         r0 = r - 4; r0 = r0 < 0 ? 0 : (r0 > 120 ? 120 : r0); }
;     else if (KIND == 1) { const int qb = u & 255, hq = (u >> 8) & 7; b = u >> 11; q0 = 32 * qb; qrow0 = b * SEQ + q0; head16 = 8 + hq; const int kvh = hq >> 2; hv = 8 + kvh;
;         sinkv = a.sink[hq]; has_sink = true; bound = fmaxf(bndB, sinkv); }
;     else { const int qblk = u & 7; head16 = (u >> 3) & 15; b = u >> 7; qrow0 = MLAT + b * CTXL + 32 * qblk;
;         if (head16 < 8) { hv = head16; bound = bndA; } else { const int kvh = (head16 - 8) >> 2; hv = 8 + kvh; sinkv = a.sink[head16 - 8]; has_sink = true; bound = fmaxf(bndB, sinkv); } }
;     const float negB = -bound * L2E;
;     if (has_sink) l = 0.5f * __builtin_amdgcn_exp2f(sinkv * L2E + negB);
;     bf16x8 qf[4], kf[2][4];
;     const bf16* qp = a.Q + (size_t)(qrow0 + r32) * DM + head16 * 64 + 8 * half;
; #pragma unroll
;     for (int kk = 0; kk < 4; ++kk) qf[kk] = *(const bf16x8*)(qp + 16 * kk);
;     f32x16 ot[2]; unsigned mw[2][8];
; #pragma unroll
;     for (int db = 0; db < 2; ++db) {
; #pragma unroll
;         for (int i = 0; i < 16; ++i) ot[db][i] = 0.f;
; #pragma unroll
;         for (int i = 0; i < 8; ++i) mw[db][i] = 0u; }
;     const bf16* kc0 = a.KC + (size_t)(b * 10 + hv) * 4 * 4096;
;     const bf16* vc0 = a.VTC + (size_t)(b * 10 + hv) * 4 * 4096;
; #pragma unroll
;     for (int kb = 0; kb < 2; ++kb)
; #pragma unroll
;         for (int kk = 0; kk < 4; ++kk) kf[kb][kk] = *(const bf16x8*)(kc0 + ((kb * 4 + kk) * 64 + lane) * 8);
;     const bf16* kl0 = a.K + (size_t)(b * 10 + hv) * 128 * 4096;
;     const bf16* vl0 = a.VT + (size_t)(b * 10 + hv) * 128 * 4096;
;     int ntl = 0, t0 = 0;
;     if (KIND == 0) { ntl = 8; t0 = r0 * 64; }
;     int ti0 = 0, nint = 0, tbA = 0, tbB = 0; bool hasA = false, hasB = false;
;     if (KIND == 1) { const int lo = (q0 - 34) & ~63; int a0 = lo, a1 = lo + 192; if (a0 < 0) a0 = 0; if (a1 > SEQ) a1 = SEQ; ti0 = a0; nint = (a1 - a0) >> 6;
;         tbA = lo - 64; hasA = tbA >= 0; tbB = lo + 192; hasB = tbB < SEQ; ntl = (hasA ? 1 : 0) + (hasB ? 1 : 0); t0 = hasA ? tbA : tbB; }
.LBB0_531:
	s_and_b32 s9, s8, 0x7f
	v_med3_u32 v16, s9, 4, v211
	s_ashr_i32 s11, s8, 10
	v_readfirstlane_b32 s12, v16
	s_lshl_b32 s17, s12, 6
	s_lshl_b32 s12, s11, 13
	s_lshl_b32 s9, s9, 6
	s_or_b32 s9, s12, s9
	s_bfe_u32 s16, s8, 0x30007
	v_or_b32_e32 v16, s9, v179
	s_mul_i32 s18, s11, 10
	v_ashrrev_i32_e32 v17, 31, v16
	s_add_i32 s12, s18, s16
	v_lshlrev_b64 v[160:161], 10, v[16:17]
	v_lshlrev_b64 v[16:17], 11, v[16:17]
	s_ashr_i32 s13, s12, 31
	s_lshr_b32 s10, s8, 7
	v_lshl_add_u64 v[16:17], s[66:67], 0, v[16:17]
	s_lshl_b32 s9, s16, 6
	s_lshl_b32 s24, s16, 7
	s_lshl_b64 s[14:15], s[12:13], 15
	v_lshl_add_u64 v[16:17], v[16:17], 0, s[24:25]
	v_lshlrev_b32_e32 v156, 1, v186
	v_mov_b32_e32 v157, v80
	s_add_u32 s14, s76, s14
	v_lshl_add_u64 v[16:17], v[16:17], 0, v[156:157]
	s_addc_u32 s15, s77, s15
	v_lshlrev_b32_e32 v158, 1, v174
	v_mov_b32_e32 v159, v80
	global_load_dwordx4 v[82:85], v[16:17], off
	global_load_dwordx4 v[86:89], v[16:17], off offset:32
	global_load_dwordx4 v[90:93], v[16:17], off offset:64
	global_load_dwordx4 v[94:97], v[16:17], off offset:96
	v_lshl_add_u64 v[16:17], s[14:15], 0, v[158:159]
	global_load_dwordx4 v[126:129], v158, s[14:15]
	global_load_dwordx4 v[118:121], v158, s[14:15] offset:1024
	global_load_dwordx4 v[114:117], v158, s[14:15] offset:2048
	global_load_dwordx4 v[102:105], v158, s[14:15] offset:3072
	global_load_dwordx4 v[110:113], v189, s[14:15]
	v_add_co_u32_e32 v16, vcc, s49, v16
	s_lshl_b64 s[12:13], s[12:13], 20
	s_nop 0
	v_addc_co_u32_e32 v17, vcc, 0, v17, vcc
	global_load_dwordx4 v[122:125], v[16:17], off offset:1024
	global_load_dwordx4 v[106:109], v[16:17], off offset:2048
	global_load_dwordx4 v[98:101], v[16:17], off offset:3072
	s_add_u32 s22, s78, s12
	s_addc_u32 s23, s79, s13
	s_add_i32 s24, s17, 0xffffff00
	s_lshr_b32 s100, s24, 6
	s_sub_u32 s100, 0, s100
	s_and_b32 s100, s100, 7
	s_lshl_b32 s100, s100, 6
	s_add_i32 s24, s24, s100
	s_lshl_b64 s[12:13], s[24:25], 7
	s_add_u32 s11, s22, s12
	s_addc_u32 s12, s23, s13
	s_ashr_i32 s13, s18, 31
	s_add_u32 s26, s18, s16
	s_addc_u32 s27, s13, 0
	s_lshl_b64 s[16:17], s[26:27], 15
	s_add_u32 s13, s58, s16
	v_mov_b32_e32 v157, 0
	s_addc_u32 s14, s59, s17
	v_lshl_add_u64 v[142:143], v[154:155], 0, s[16:17]
	s_mov_b64 s[28:29], 0
	v_mov_b32_e32 v32, 0
	v_mov_b32_e32 v33, v157
	v_mov_b32_e32 v34, v157
	v_mov_b32_e32 v35, v157
	v_mov_b32_e32 v36, v157
	v_mov_b32_e32 v37, v157
	v_mov_b32_e32 v38, v157
	v_mov_b32_e32 v39, v157
	v_mov_b32_e32 v40, v157
	v_mov_b32_e32 v41, v157
	v_mov_b32_e32 v42, v157
	v_mov_b32_e32 v43, v157
	v_mov_b32_e32 v44, v157
	v_mov_b32_e32 v45, v157
	v_mov_b32_e32 v46, v157
	v_mov_b32_e32 v47, v157
	v_mov_b32_e32 v16, 0
	v_mov_b32_e32 v17, v157
	v_mov_b32_e32 v18, v157
	v_mov_b32_e32 v19, v157
	v_mov_b32_e32 v20, v157
	v_mov_b32_e32 v21, v157
	v_mov_b32_e32 v22, v157
	v_mov_b32_e32 v23, v157
	v_mov_b32_e32 v24, v157
	v_mov_b32_e32 v25, v157
	v_mov_b32_e32 v26, v157
	v_mov_b32_e32 v27, v157
	v_mov_b32_e32 v28, v157
	v_mov_b32_e32 v29, v157
	v_mov_b32_e32 v30, v157
	v_mov_b32_e32 v31, v157
.LBB0_532:
	s_waitcnt vmcnt(7)
	v_mfma_f32_32x32x16_bf16 v[64:79], v[126:129], v[82:85], v[0:15]
	v_lshl_add_u64 v[126:127], v[142:143], 0, s[28:29]
	s_add_u32 s15, s13, s28
	s_addc_u32 s16, s14, s29
	s_add_u32 s15, s15, 0x15202000
	s_addc_u32 s16, s16, 0
	s_cmpk_eq_i32 s28, 0x6000
	s_cselect_b32 s31, s12, s16
	s_waitcnt vmcnt(3)
	v_mfma_f32_32x32x16_bf16 v[48:63], v[110:113], v[82:85], v[0:15]
	v_add_co_u32_e32 v110, vcc, s47, v126
	s_cselect_b32 s30, s11, s15
	s_nop 0
	v_addc_co_u32_e32 v111, vcc, 0, v127, vcc
	v_add_co_u32_e32 v112, vcc, s4, v126
	v_mfma_f32_32x32x16_bf16 v[64:79], v[118:121], v[86:89], v[64:79]
	s_nop 0
	v_addc_co_u32_e32 v113, vcc, 0, v127, vcc
	global_load_dwordx4 v[144:147], v[112:113], off offset:-4096
	global_load_dwordx4 v[148:151], v[112:113], off
	global_load_dwordx4 v[190:193], v[110:111], off offset:1024
	global_load_dwordx4 v[134:137], v[110:111], off offset:2048
	global_load_dwordx4 v[236:239], v[112:113], off offset:1024
	global_load_dwordx4 v[138:141], v[110:111], off offset:3072
	global_load_dwordx4 v[240:243], v[112:113], off offset:2048
	global_load_dwordx4 v[130:133], v[112:113], off offset:3072
	s_waitcnt vmcnt(10)
	v_mfma_f32_32x32x16_bf16 v[48:63], v[122:125], v[86:89], v[48:63]
	global_load_dwordx4 v[126:129], v158, s[30:31]
	global_load_dwordx4 v[110:113], v189, s[30:31]
	s_add_u32 s28, s28, 0x2000
	s_addc_u32 s29, s29, 0
	s_cmpk_eq_u32 s28, 0x8000
	v_mfma_f32_32x32x16_bf16 v[64:79], v[114:117], v[90:93], v[64:79]
	s_waitcnt vmcnt(11)
	v_mfma_f32_32x32x16_bf16 v[48:63], v[106:109], v[90:93], v[48:63]
	v_mfma_f32_32x32x16_bf16 v[64:79], v[102:105], v[94:97], v[64:79]
	global_load_dwordx4 v[118:121], v158, s[30:31] offset:1024
	global_load_dwordx4 v[122:125], v194, s[30:31]
	global_load_dwordx4 v[106:109], v195, s[30:31]
	global_load_dwordx4 v[114:117], v158, s[30:31] offset:2048
	global_load_dwordx4 v[102:105], v158, s[30:31] offset:3072
	s_nop 6
	v_exp_f32_e32 v64, v64
	s_waitcnt vmcnt(15)
	v_mfma_f32_32x32x16_bf16 v[48:63], v[98:101], v[94:97], v[48:63]
	global_load_dwordx4 v[98:101], v212, s[30:31]
	v_exp_f32_e32 v65, v65
	v_exp_f32_e32 v66, v66
	v_exp_f32_e32 v67, v67
	v_exp_f32_e32 v68, v68
	v_exp_f32_e32 v69, v69
	v_exp_f32_e32 v70, v70
	v_exp_f32_e32 v71, v71
	s_nop 3
	v_exp_f32_e32 v81, v48
	v_exp_f32_e32 v152, v49
	v_exp_f32_e32 v153, v50
	v_exp_f32_e32 v159, v51
	v_cvt_pk_bf16_f32 v48, v64, v65
	v_cvt_pk_bf16_f32 v49, v66, v67
	v_cvt_pk_bf16_f32 v50, v68, v69
	v_cvt_pk_bf16_f32 v51, v70, v71
	v_exp_f32_e32 v72, v72
	v_exp_f32_e32 v73, v73
	v_exp_f32_e32 v74, v74
	v_exp_f32_e32 v75, v75
	v_exp_f32_e32 v76, v76
	v_exp_f32_e32 v77, v77
	v_exp_f32_e32 v78, v78
	v_exp_f32_e32 v79, v79
	v_add_f32_e32 v64, 0, v64
	v_exp_f32_e32 v244, v52
	s_waitcnt vmcnt(15)
; template <int MASK, int QH> ...
;     ...
;     for (int kb = 0; kb < 2; ++kb)
; #pragma unroll
;         for (int hs = 0; hs < 2; ++hs) {
;             if (!ATT_KS_LIVE(2 * kb + hs)) continue;
;             float pv[8];
; #pragma unroll
;             for (int j = 0; j < 8; ++j) {
;                 const int i = 8 * hs + j, kc = 32 * kb + 8 * (i >> 2) + (i & 3);
;                 if (!ATT_LIVE(kb, i)) { pv[j] = 0.f; continue; }
;                 float s = st[kb][i];
;                 if (MASK == 1) s += tab[mp1 + kc];
;                 float pe = __builtin_amdgcn_exp2f(s);
;                 if (MASK == 2) pe = ((unsigned)(kc + mp0) <= 256u) ? pe : 0.f;
;                 pv[j] = pe; if (MASK != 1) ls += pe;
;             }
;             v4u w; w.x = pk2(pv[0], pv[1]); w.y = pk2(pv[2], pv[3]); w.z = pk2(pv[4], pv[5]); w.w = pk2(pv[6], pv[7]);
;             if (MASK == 1) {
;                 unsigned wm[4] = {w.x, w.y, w.z, w.w};
; #pragma unroll
;                 for (int t = 0; t < 4; ++t) { if (!ATT_LIVE(kb, 8 * hs + 2 * t)) { wm[t] = 0u; continue; }
;                     wm[t] &= mw[kb][4 * hs + t];
;                     ls += __uint_as_float(wm[t] << 16); ls += __uint_as_float(wm[t] & 0xffff0000u); }
;                 w.x = wm[0]; w.y = wm[1]; w.z = wm[2]; w.w = wm[3];
;             }
;             pf[2 * kb + hs] = __builtin_bit_cast(bf16x8, w);
;         }
;     l += ls;
; #pragma unroll
;     for (int db = 0; db < 2; ++db)
; #pragma unroll
;         for (int ks = 0; ks < 4; ++ks) if (ATT_KS_LIVE(ks)) ot[db] = __builtin_amdgcn_mfma_f32_32x32x16_bf16(vfr[db][ks], pf[ks], ot[db], 0, 0, 0);
; template <int KIND, int QH>
; __device__ __forceinline__ void attn_unit(const AttnBufs& a, int u, int lane, const LAS float* rpbt, float bndA, float bndB) {
;     ...
;     if (KIND == 0) {
;         const int c = QH * 32 + r32; int c0 = c - 8; c0 = c0 < 0 ? 0 : (c0 > 48 ? 48 : c0);
; #pragma unroll
;         for (int kb = 0; kb < 2; ++kb)
; #pragma unroll
;             for (int pp = 0; pp < 8; ++pp) { const int i = 2 * pp, kc = 32 * kb + 8 * (i >> 2) + (i & 3) + 4 * half - c0;
;                 mw[kb][pp] = ((unsigned)kc < 16u ? 0x0000ffffu : 0u) | ((unsigned)(kc + 1) < 16u ? 0xffff0000u : 0u); }
; #pragma unroll 1
;         for (int i = 0; i < 8; ++i) {
;             const int tk = t0 + 64 * i; const bf16* kn = kl0 + (size_t)(i < 7 ? tk + 64 : tk) * 64;
	v_mfma_f32_32x32x16_bf16 v[32:47], v[144:147], v[48:51], v[32:47]
	v_exp_f32_e32 v144, v53
	v_exp_f32_e32 v145, v54
	v_exp_f32_e32 v146, v55
	v_cvt_pk_bf16_f32 v52, v81, v152
	v_cvt_pk_bf16_f32 v53, v153, v159
	v_cvt_pk_bf16_f32 v54, v244, v144
	v_cvt_pk_bf16_f32 v55, v145, v146
	s_waitcnt vmcnt(14)
	v_mfma_f32_32x32x16_bf16 v[16:31], v[148:151], v[48:51], v[16:31]
	v_cvt_pk_bf16_f32 v48, v72, v73
	v_cvt_pk_bf16_f32 v49, v74, v75
	v_cvt_pk_bf16_f32 v50, v76, v77
	v_cvt_pk_bf16_f32 v51, v78, v79
	v_exp_f32_e32 v147, v56
	v_exp_f32_e32 v245, v57
	v_exp_f32_e32 v246, v58
	s_waitcnt vmcnt(13)
	v_mfma_f32_32x32x16_bf16 v[32:47], v[190:193], v[48:51], v[32:47]
	v_exp_f32_e32 v247, v59
	v_exp_f32_e32 v60, v60
	v_exp_f32_e32 v61, v61
	v_exp_f32_e32 v62, v62
	v_exp_f32_e32 v63, v63
	v_cvt_pk_bf16_f32 v56, v147, v245
	v_cvt_pk_bf16_f32 v57, v246, v247
	s_waitcnt vmcnt(11)
	v_mfma_f32_32x32x16_bf16 v[16:31], v[236:239], v[48:51], v[16:31]
	v_add_f32_e32 v48, v65, v64
	v_add_f32_e32 v48, v66, v48
	v_add_f32_e32 v48, v67, v48
	v_add_f32_e32 v48, v68, v48
	v_add_f32_e32 v48, v69, v48
	v_add_f32_e32 v48, v70, v48
	v_add_f32_e32 v48, v71, v48
	v_add_f32_e32 v48, v72, v48
	v_add_f32_e32 v48, v73, v48
	v_add_f32_e32 v48, v74, v48
	v_add_f32_e32 v48, v75, v48
	v_add_f32_e32 v48, v76, v48
	v_add_f32_e32 v48, v77, v48
	v_add_f32_e32 v48, v78, v48
	v_add_f32_e32 v48, v79, v48
	v_add_f32_e32 v48, v81, v48
	v_mfma_f32_32x32x16_bf16 v[32:47], v[134:137], v[52:55], v[32:47]
	v_add_f32_e32 v48, v152, v48
	v_add_f32_e32 v48, v153, v48
	v_add_f32_e32 v48, v159, v48
	v_add_f32_e32 v48, v244, v48
	v_add_f32_e32 v48, v144, v48
	v_add_f32_e32 v48, v145, v48
	v_add_f32_e32 v48, v146, v48
	s_waitcnt vmcnt(9)
	v_mfma_f32_32x32x16_bf16 v[16:31], v[240:243], v[52:55], v[16:31]
	v_cvt_pk_bf16_f32 v58, v60, v61
	v_cvt_pk_bf16_f32 v59, v62, v63
	v_add_f32_e32 v48, v147, v48
	v_add_f32_e32 v48, v245, v48
	v_add_f32_e32 v48, v246, v48
	v_add_f32_e32 v48, v247, v48
	v_add_f32_e32 v48, v60, v48
	v_mfma_f32_32x32x16_bf16 v[32:47], v[138:141], v[56:59], v[32:47]
	v_add_f32_e32 v48, v61, v48
	v_add_f32_e32 v48, v62, v48
	v_add_f32_e32 v48, v63, v48
	v_add_f32_e32 v157, v157, v48
	s_waitcnt vmcnt(8)
	v_mfma_f32_32x32x16_bf16 v[16:31], v[130:133], v[56:59], v[16:31]
	s_cbranch_scc0 .LBB0_532
	s_and_b32 s11, s3, 0x7f
	s_and_b32 s10, s10, 7
	v_med3_u32 v49, s11, 4, v211
	s_movk_i32 s12, 0x7c
	s_mulk_i32 s10, 0xa00
	v_mul_lo_u32 v48, v49, s12
	v_add_u32_e32 v48, s10, v48
	s_mulk_i32 s11, 0x7c
	v_subrev_u32_e32 v48, s11, v48
	v_add_u32_e32 v236, v235, v48
	v_mov_b32_e32 v48, s3
	v_mov_b32_e32 v159, v80
	v_readfirstlane_b32 s10, v48
	s_and_b32 s24, s10, 0x7f
	v_cmp_gt_u64_e64 s[10:11], s[24:25], 4
	s_and_b64 s[10:11], s[10:11], exec
	s_cselect_b32 s24, s24, 4
	v_cmp_lt_u64_e32 vcc, s[24:25], v[170:171]
	s_and_b64 s[10:11], vcc, exec
	s_cselect_b32 s10, s24, 0x7c
	s_lshl_b32 s10, s10, 13
	v_readfirstlane_b32 s11, v49
	s_lshl_b64 s[12:13], s[26:27], 20
	s_lshl_b32 s11, s11, 6
	s_or_b32 s12, s12, s10
	s_addk_i32 s11, 0xff00
	v_lshl_add_u64 v[190:191], s[22:23], 0, v[158:159]
	v_lshl_add_u64 v[192:193], v[154:155], 0, s[12:13]
	s_lshr_b32 s100, s11, 6
	s_sub_u32 s100, 0, s100
	s_and_b32 s100, s100, 7
	s_lshl_b32 s22, s100, 13
	s_mov_b32 s23, 0
	s_lshl_b32 s101, s100, 6
	s_add_i32 s11, s11, s101
	s_mulk_i32 s100, 0x7c
	v_add_u32_e32 v236, s100, v236
	s_mov_b32 s100, s22
.LBB0_534:
	v_lshl_add_u64 v[48:49], v[192:193], 0, s[22:23]
	v_add_co_u32_e32 v50, vcc, s5, v48
	s_waitcnt vmcnt(7)
	v_mfma_f32_32x32x16_bf16 v[64:79], v[126:129], v[82:85], v[0:15]
	v_addc_co_u32_e32 v51, vcc, 0, v49, vcc
	v_add_co_u32_e32 v48, vcc, s6, v48
	s_nop 0
	v_addc_co_u32_e32 v49, vcc, 0, v49, vcc
	global_load_dwordx4 v[130:133], v[48:49], off offset:-4096
	global_load_dwordx4 v[134:137], v[50:51], off offset:1024
	global_load_dwordx4 v[138:141], v[50:51], off offset:2048
	global_load_dwordx4 v[142:145], v[48:49], off
	global_load_dwordx4 v[146:149], v[48:49], off offset:1024
	global_load_dwordx4 v[150:153], v[48:49], off offset:2048
	s_waitcnt vmcnt(9)
	v_mfma_f32_32x32x16_bf16 v[48:63], v[110:113], v[82:85], v[0:15]
	s_add_u32 s22, s22, 0x2000
	s_and_b32 s22, s22, 0xffff
	s_cmp_eq_u32 s22, 0
	s_cselect_b32 s12, 0xfffffe40, 64
	s_cselect_b32 s101, 0x3e0, 0
	s_add_i32 s10, s11, s12
	s_mov_b32 s12, s10
	s_ashr_i32 s13, s12, 31
	s_lshl_b64 s[26:27], s[12:13], 7
	v_mov_b32_e32 v81, v80
	s_waitcnt vmcnt(8)
	v_mfma_f32_32x32x16_bf16 v[48:63], v[122:125], v[86:89], v[48:63]
	s_cmp_lg_u32 s22, s100
	s_mov_b32 s11, s10
	v_mfma_f32_32x32x16_bf16 v[64:79], v[118:121], v[86:89], v[64:79]
	s_waitcnt vmcnt(7)
	v_mfma_f32_32x32x16_bf16 v[48:63], v[106:109], v[90:93], v[48:63]
	s_waitcnt vmcnt(8)
	v_mfma_f32_32x32x16_bf16 v[64:79], v[114:117], v[90:93], v[64:79]
	s_waitcnt vmcnt(6)
	v_mfma_f32_32x32x16_bf16 v[48:63], v[98:101], v[94:97], v[48:63]
	v_mfma_f32_32x32x16_bf16 v[64:79], v[102:105], v[94:97], v[64:79]
	s_nop 10
	v_lshl_add_u64 v[52:53], v[190:191], 0, s[26:27]
	global_load_dwordx4 v[126:129], v[52:53], off
	global_load_dwordx4 v[118:121], v[52:53], off offset:1024
	global_load_dwordx4 v[114:117], v[52:53], off offset:2048
	global_load_dwordx4 v[102:105], v[52:53], off offset:3072
	v_add_co_u32_e32 v52, vcc, s49, v52
	s_nop 1
	v_addc_co_u32_e32 v53, vcc, 0, v53, vcc
	global_load_dwordx4 v[110:113], v[52:53], off
	global_load_dwordx4 v[122:125], v[52:53], off offset:1024
	global_load_dwordx4 v[106:109], v[52:53], off offset:2048
	global_load_dwordx4 v[98:101], v[52:53], off offset:3072
	ds_read2_b32 v[52:53], v236 offset1:1
	s_waitcnt lgkmcnt(0)
; __device__ __forceinline__ unsigned pk2(float lo, float hi) { return __builtin_bit_cast(unsigned, __builtin_convertvector((f32x2_t){lo, hi}, bf16x2_t)); }
; #define ATT_KS_LIVE(ks) (ATT_LIVE((ks) >> 1, 8 * ((ks) & 1)) || ATT_LIVE((ks) >> 1, 8 * ((ks) & 1) + 4))
; template <int MASK, int QH> ...
;     ...
;             float pv[8];
; #pragma unroll
;             for (int j = 0; j < 8; ++j) {
;                 const int i = 8 * hs + j, kc = 32 * kb + 8 * (i >> 2) + (i & 3);
;                 if (!ATT_LIVE(kb, i)) { pv[j] = 0.f; continue; }
;                 float s = st[kb][i];
;                 if (MASK == 1) s += tab[mp1 + kc];
;                 float pe = __builtin_amdgcn_exp2f(s);
;                 if (MASK == 2) pe = ((unsigned)(kc + mp0) <= 256u) ? pe : 0.f;
;                 pv[j] = pe; if (MASK != 1) ls += pe;
;             }
;             v4u w; w.x = pk2(pv[0], pv[1]); w.y = pk2(pv[2], pv[3]); w.z = pk2(pv[4], pv[5]); w.w = pk2(pv[6], pv[7]);
;             if (MASK == 1) {
;                 unsigned wm[4] = {w.x, w.y, w.z, w.w};
; #pragma unroll
;                 for (int t = 0; t < 4; ++t) { if (!ATT_LIVE(kb, 8 * hs + 2 * t)) { wm[t] = 0u; continue; }
;                     wm[t] &= mw[kb][4 * hs + t];
;                     ls += __uint_as_float(wm[t] << 16); ls += __uint_as_float(wm[t] & 0xffff0000u); }
;                 w.x = wm[0]; w.y = wm[1]; w.z = wm[2]; w.w = wm[3];
;             }
;             pf[2 * kb + hs] = __builtin_bit_cast(bf16x8, w);
;         }
;     l += ls;
; #pragma unroll
;     for (int db = 0; db < 2; ++db)
; #pragma unroll
;         for (int ks = 0; ks < 4; ++ks) if (ATT_KS_LIVE(ks)) ot[db] = __builtin_amdgcn_mfma_f32_32x32x16_bf16(vfr[db][ks], pf[ks], ot[db], 0, 0, 0);
; template <int KIND, int QH>
; __device__ __forceinline__ void attn_unit(const AttnBufs& a, int u, int lane, const LAS float* rpbt, float bndA, float bndB) {
;     ...
;     l += __shfl_xor(l, 32);
;     const float inv = 1.0f / l;
;     bf16* op = a.O + (size_t)(qrow0 + r32) * DM + head16 * 64 + 4 * half;
; #pragma unroll
;     for (int db = 0; db < 2; ++db)
; #pragma unroll
;         for (int g = 0; g < 4; ++g) { v2u w; w.x = pk2(ot[db][4 * g] * inv, ot[db][4 * g + 1] * inv); w.y = pk2(ot[db][4 * g + 2] * inv, ot[db][4 * g + 3] * inv);
;             *(v2u*)(op + 32 * db + 8 * g) = w; }
	v_add_f32_e32 v52, v64, v52
	v_exp_f32_e32 v54, v52
	v_add_f32_e32 v52, v65, v53
	v_exp_f32_e32 v55, v52
	ds_read2_b32 v[52:53], v236 offset0:2 offset1:3
	v_cvt_pk_bf16_f32 v54, v54, v55
	s_waitcnt lgkmcnt(0)
	v_add_f32_e32 v52, v66, v52
	v_exp_f32_e32 v56, v52
	v_add_f32_e32 v52, v67, v53
	v_exp_f32_e32 v57, v52
	ds_read2_b32 v[52:53], v236 offset0:8 offset1:9
	v_cvt_pk_bf16_f32 v55, v56, v57
	s_waitcnt lgkmcnt(0)
	v_add_f32_e32 v52, v68, v52
	v_exp_f32_e32 v58, v52
	v_add_f32_e32 v52, v69, v53
	v_exp_f32_e32 v59, v52
	ds_read2_b32 v[52:53], v236 offset0:10 offset1:11
	v_cvt_pk_bf16_f32 v56, v58, v59
	s_waitcnt lgkmcnt(0)
	v_add_f32_e32 v52, v70, v52
	v_add_f32_e32 v53, v71, v53
	v_exp_f32_e32 v52, v52
	v_exp_f32_e32 v53, v53
	s_nop 0
	v_cvt_pk_bf16_f32 v57, v52, v53
	v_and_b32_e32 v52, v216, v54
	v_lshlrev_b32_e32 v53, 16, v52
	v_add_f32_e32 v53, 0, v53
	v_and_b32_e32 v54, v215, v54
	v_add_f32_e32 v54, v53, v54
	v_and_b32_e32 v53, v218, v55
	v_lshlrev_b32_e32 v58, 16, v53
	v_add_f32_e32 v54, v54, v58
	v_and_b32_e32 v55, v217, v55
	v_add_f32_e32 v55, v54, v55
	v_and_b32_e32 v54, v220, v56
	v_lshlrev_b32_e32 v58, 16, v54
	v_add_f32_e32 v55, v55, v58
	v_and_b32_e32 v56, v219, v56
	v_add_f32_e32 v56, v55, v56
	v_and_b32_e32 v55, v222, v57
	v_lshlrev_b32_e32 v58, 16, v55
	v_add_f32_e32 v56, v56, v58
	v_and_b32_e32 v57, v221, v57
	v_add_f32_e32 v58, v56, v57
	ds_read2_b32 v[56:57], v236 offset0:16 offset1:17
	s_waitcnt vmcnt(13)
	v_mfma_f32_32x32x16_bf16 v[32:47], v[130:133], v[52:55], v[32:47]
	s_waitcnt lgkmcnt(0)
	v_add_f32_e32 v56, v72, v56
	v_exp_f32_e32 v59, v56
	v_add_f32_e32 v56, v73, v57
	v_exp_f32_e32 v60, v56
	ds_read2_b32 v[56:57], v236 offset0:18 offset1:19
	s_waitcnt vmcnt(10)
	v_mfma_f32_32x32x16_bf16 v[16:31], v[142:145], v[52:55], v[16:31]
	v_cvt_pk_bf16_f32 v59, v59, v60
	s_waitcnt lgkmcnt(0)
	v_add_f32_e32 v56, v74, v56
	v_exp_f32_e32 v61, v56
	v_add_f32_e32 v56, v75, v57
	v_exp_f32_e32 v62, v56
	ds_read2_b32 v[56:57], v236 offset0:24 offset1:25
	v_cvt_pk_bf16_f32 v60, v61, v62
	s_waitcnt lgkmcnt(0)
	v_add_f32_e32 v56, v76, v56
	v_exp_f32_e32 v63, v56
	v_add_f32_e32 v56, v77, v57
	v_exp_f32_e32 v64, v56
	ds_read2_b32 v[56:57], v236 offset0:26 offset1:27
	v_cvt_pk_bf16_f32 v61, v63, v64
	s_waitcnt lgkmcnt(0)
	v_add_f32_e32 v56, v78, v56
	v_add_f32_e32 v57, v79, v57
	v_exp_f32_e32 v56, v56
	v_exp_f32_e32 v57, v57
	s_nop 0
	v_cvt_pk_bf16_f32 v62, v56, v57
	v_and_b32_e32 v56, v224, v59
	v_lshlrev_b32_e32 v57, 16, v56
	v_add_f32_e32 v57, v58, v57
	v_and_b32_e32 v58, v223, v59
	v_add_f32_e32 v58, v57, v58
	v_and_b32_e32 v57, v226, v60
	v_lshlrev_b32_e32 v59, 16, v57
	v_add_f32_e32 v58, v58, v59
	v_and_b32_e32 v59, v225, v60
	v_add_f32_e32 v59, v58, v59
	v_and_b32_e32 v58, v228, v61
	v_lshlrev_b32_e32 v60, 16, v58
	v_add_f32_e32 v59, v59, v60
	v_and_b32_e32 v60, v227, v61
	v_add_f32_e32 v60, v59, v60
	v_and_b32_e32 v59, v230, v62
	v_lshlrev_b32_e32 v61, 16, v59
	v_add_f32_e32 v60, v60, v61
	v_and_b32_e32 v61, v229, v62
	v_add_f32_e32 v62, v60, v61
	ds_read2_b32 v[60:61], v236 offset0:32 offset1:33
	v_mfma_f32_32x32x16_bf16 v[32:47], v[134:137], v[56:59], v[32:47]
	s_waitcnt lgkmcnt(0)
	v_add_f32_e32 v48, v48, v60
	v_exp_f32_e32 v60, v48
	v_add_f32_e32 v48, v49, v61
	v_exp_f32_e32 v61, v48
	ds_read2_b32 v[48:49], v236 offset0:34 offset1:35
	s_waitcnt vmcnt(9)
	v_mfma_f32_32x32x16_bf16 v[16:31], v[146:149], v[56:59], v[16:31]
	v_add_u32_e32 v236, 0x7c, v236
	v_subrev_u32_e32 v236, s101, v236
	s_waitcnt lgkmcnt(0)
	v_add_f32_e32 v48, v50, v48
	v_add_f32_e32 v49, v51, v49
	v_exp_f32_e32 v48, v48
	v_exp_f32_e32 v49, v49
	s_nop 0
	v_cvt_pk_bf16_f32 v48, v48, v49
	v_cvt_pk_bf16_f32 v49, v60, v61
	v_and_b32_e32 v78, v232, v49
	v_and_b32_e32 v79, v234, v48
	v_lshlrev_b32_e32 v50, 16, v78
	v_add_f32_e32 v50, v62, v50
	v_mfma_f32_32x32x16_bf16 v[32:47], v[138:141], v[78:81], v[32:47]
	v_and_b32_e32 v49, v231, v49
	v_add_f32_e32 v49, v50, v49
	v_lshlrev_b32_e32 v50, 16, v79
	v_add_f32_e32 v49, v49, v50
	v_and_b32_e32 v48, v233, v48
	v_add_f32_e32 v48, v49, v48
	v_add_f32_e32 v157, v157, v48
	s_waitcnt vmcnt(8)
	v_mfma_f32_32x32x16_bf16 v[16:31], v[150:153], v[78:81], v[16:31]
	s_cbranch_scc1 .LBB0_534
	ds_bpermute_b32 v50, v175, v157
	v_lshl_add_u64 v[48:49], v[160:161], 1, s[68:69]
	s_lshl_b32 s24, s9, 1
	v_lshl_add_u64 v[48:49], v[48:49], 0, s[24:25]
	v_lshlrev_b32_e32 v142, 1, v176
	s_waitcnt lgkmcnt(0)
	v_add_f32_e32 v50, v157, v50
	v_div_scale_f32 v51, s[10:11], v50, v50, 1.0
	v_rcp_f32_e32 v52, v51
	v_div_scale_f32 v53, vcc, 1.0, v50, 1.0
	v_mov_b32_e32 v143, v80
	v_fma_f32 v54, -v51, v52, 1.0
	v_fmac_f32_e32 v52, v54, v52
	v_mul_f32_e32 v54, v53, v52
	v_fma_f32 v55, -v51, v54, v53
	v_fmac_f32_e32 v54, v55, v52
	v_fma_f32 v51, -v51, v54, v53
	v_div_fmas_f32 v51, v51, v52, v54
	v_div_fixup_f32 v50, v51, v50, 1.0
	v_pk_mul_f32 v[32:33], v[32:33], v[50:51] op_sel_hi:[1,0]
	v_pk_mul_f32 v[34:35], v[34:35], v[50:51] op_sel_hi:[1,0]
	v_pk_mul_f32 v[16:17], v[16:17], v[50:51] op_sel_hi:[1,0]
	v_pk_mul_f32 v[18:19], v[18:19], v[50:51] op_sel_hi:[1,0]
	v_lshl_add_u64 v[48:49], v[48:49], 0, v[142:143]
	v_cvt_pk_bf16_f32 v32, v32, v33
	v_cvt_pk_bf16_f32 v33, v34, v35
	v_cvt_pk_bf16_f32 v16, v16, v17
	v_cvt_pk_bf16_f32 v17, v18, v19
	global_store_dwordx2 v[48:49], v[32:33], off
	v_pk_mul_f32 v[32:33], v[36:37], v[50:51] op_sel_hi:[1,0]
	v_pk_mul_f32 v[34:35], v[38:39], v[50:51] op_sel_hi:[1,0]
	global_store_dwordx2 v[48:49], v[16:17], off offset:64
	v_pk_mul_f32 v[16:17], v[20:21], v[50:51] op_sel_hi:[1,0]
	v_pk_mul_f32 v[18:19], v[22:23], v[50:51] op_sel_hi:[1,0]
	v_cvt_pk_bf16_f32 v32, v32, v33
	v_cvt_pk_bf16_f32 v33, v34, v35
	v_cvt_pk_bf16_f32 v16, v16, v17
	v_cvt_pk_bf16_f32 v17, v18, v19
	global_store_dwordx2 v[48:49], v[32:33], off offset:16
	v_pk_mul_f32 v[32:33], v[40:41], v[50:51] op_sel_hi:[1,0]
	v_pk_mul_f32 v[34:35], v[42:43], v[50:51] op_sel_hi:[1,0]
	global_store_dwordx2 v[48:49], v[16:17], off offset:80
	v_pk_mul_f32 v[16:17], v[24:25], v[50:51] op_sel_hi:[1,0]
	v_pk_mul_f32 v[18:19], v[26:27], v[50:51] op_sel_hi:[1,0]
	v_cvt_pk_bf16_f32 v32, v32, v33
	v_cvt_pk_bf16_f32 v33, v34, v35
	v_cvt_pk_bf16_f32 v16, v16, v17
	v_cvt_pk_bf16_f32 v17, v18, v19
	global_store_dwordx2 v[48:49], v[32:33], off offset:32
	v_pk_mul_f32 v[32:33], v[44:45], v[50:51] op_sel_hi:[1,0]
	v_pk_mul_f32 v[34:35], v[46:47], v[50:51] op_sel_hi:[1,0]
	global_store_dwordx2 v[48:49], v[16:17], off offset:96
	v_pk_mul_f32 v[16:17], v[28:29], v[50:51] op_sel_hi:[1,0]
	v_pk_mul_f32 v[18:19], v[30:31], v[50:51] op_sel_hi:[1,0]
	s_add_i32 s8, s8, s84
	s_add_i32 s3, s3, s84
	v_cvt_pk_bf16_f32 v32, v32, v33
	v_cvt_pk_bf16_f32 v33, v34, v35
	v_cvt_pk_bf16_f32 v16, v16, v17
	v_cvt_pk_bf16_f32 v17, v18, v19
	s_cmpk_gt_i32 s8, 0xfff
	global_store_dwordx2 v[48:49], v[32:33], off offset:48
	global_store_dwordx2 v[48:49], v[16:17], off offset:112
	s_cbranch_scc0 .LBB0_531
; template <int KIND, int QH>
; __device__ __forceinline__ void attn_unit(const AttnBufs& a, int u, int lane, const LAS float* rpbt, float bndA, float bndB) {
;     ...
;     if (KIND == 0) { r = u & 127; h = (u >> 7) & 7; b = u >> 10; qrow0 = b * SEQ + r * 64 + 32 * QH; head16 = h; hv = h; bound = bndA;
;         r0 = r - 4; r0 = r0 < 0 ? 0 : (r0 > 120 ? 120 : r0); }
;     else if (KIND == 1) { const int qb = u & 255, hq = (u >> 8) & 7; b = u >> 11; q0 = 32 * qb; qrow0 = b * SEQ + q0; head16 = 8 + hq; const int kvh = hq >> 2; hv = 8 + kvh;
;         sinkv = a.sink[hq]; has_sink = true; bound = fmaxf(bndB, sinkv); }
;     else { const int qblk = u & 7; head16 = (u >> 3) & 15; b = u >> 7; qrow0 = MLAT + b * CTXL + 32 * qblk;
;         if (head16 < 8) { hv = head16; bound = bndA; } else { const int kvh = (head16 - 8) >> 2; hv = 8 + kvh; sinkv = a.sink[head16 - 8]; has_sink = true; bound = fmaxf(bndB, sinkv); } }
;     const float negB = -bound * L2E;
;     if (has_sink) l = 0.5f * __builtin_amdgcn_exp2f(sinkv * L2E + negB);
;     bf16x8 qf[4], kf[2][4];
;     const bf16* qp = a.Q + (size_t)(qrow0 + r32) * DM + head16 * 64 + 8 * half;
; #pragma unroll
;     for (int kk = 0; kk < 4; ++kk) qf[kk] = *(const bf16x8*)(qp + 16 * kk);
;     f32x16 ot[2]; unsigned mw[2][8];
; #pragma unroll
;     for (int db = 0; db < 2; ++db) {
; #pragma unroll
;         for (int i = 0; i < 16; ++i) ot[db][i] = 0.f;
; #pragma unroll
;         for (int i = 0; i < 8; ++i) mw[db][i] = 0u; }
;     const bf16* kc0 = a.KC + (size_t)(b * 10 + hv) * 4 * 4096;
;     const bf16* vc0 = a.VTC + (size_t)(b * 10 + hv) * 4 * 4096;
; #pragma unroll
;     for (int kb = 0; kb < 2; ++kb)
; #pragma unroll
;         for (int kk = 0; kk < 4; ++kk) kf[kb][kk] = *(const bf16x8*)(kc0 + ((kb * 4 + kk) * 64 + lane) * 8);
;     const bf16* kl0 = a.K + (size_t)(b * 10 + hv) * 128 * 4096;
;     const bf16* vl0 = a.VT + (size_t)(b * 10 + hv) * 128 * 4096;
;     int ntl = 0, t0 = 0;
;     ...
;         const int c = QH * 32 + r32; int c0 = c - 8; c0 = c0 < 0 ? 0 : (c0 > 48 ? 48 : c0);
; #pragma unroll
;         for (int kb = 0; kb < 2; ++kb)
; #pragma unroll
;             for (int pp = 0; pp < 8; ++pp) { const int i = 2 * pp, kc = 32 * kb + 8 * (i >> 2) + (i & 3) + 4 * half - c0;
;                 mw[kb][pp] = ((unsigned)kc < 16u ? 0x0000ffffu : 0u) | ((unsigned)(kc + 1) < 16u ? 0xffff0000u : 0u); }
	v_or_b32_e32 v81, 32, v213
	v_add_u32_e32 v16, -8, v81
	v_min_u32_e32 v16, 48, v16
	v_sub_u32_e32 v16, v176, v16
	v_add_u32_e32 v17, 24, v16
	v_cmp_gt_u32_e32 vcc, 16, v17
	v_add_u32_e32 v18, 25, v16
	s_movk_i32 s3, 0xffe0
	v_cndmask_b32_e32 v17, 0, v209, vcc
	v_cmp_gt_u32_e32 vcc, 16, v18
	v_add_u32_e32 v18, 27, v16
	v_add_u32_e32 v19, 33, v16
	v_cndmask_b32_e32 v148, 0, v210, vcc
	v_or_b32_e32 v149, v148, v17
	v_add_u32_e32 v17, 26, v16
	v_cmp_gt_u32_e32 vcc, 16, v17
	s_nop 1
	v_cndmask_b32_e32 v17, 0, v209, vcc
	v_cmp_gt_u32_e32 vcc, 16, v18
	s_nop 1
	v_cndmask_b32_e32 v150, 0, v210, vcc
	v_or_b32_e32 v151, v150, v17
	v_and_b32_e32 v17, -16, v16
	v_cmp_eq_u32_e32 vcc, s3, v17
	s_movk_i32 s3, 0xffd0
	s_nop 0
	v_cndmask_b32_e32 v18, 0, v209, vcc
	v_cmp_gt_u32_e32 vcc, 16, v19
	v_add_u32_e32 v19, 35, v16
	s_nop 0
	v_cndmask_b32_e32 v152, 0, v210, vcc
	v_or_b32_e32 v153, v152, v18
	v_add_u32_e32 v18, 34, v16
	v_cmp_gt_u32_e32 vcc, 16, v18
	s_nop 1
	v_cndmask_b32_e32 v18, 0, v209, vcc
	v_cmp_gt_u32_e32 vcc, 16, v19
	v_add_u32_e32 v19, 41, v16
	s_nop 0
	v_cndmask_b32_e32 v160, 0, v210, vcc
	v_or_b32_e32 v161, v160, v18
	v_add_u32_e32 v18, 40, v16
	v_cmp_gt_u32_e32 vcc, 16, v18
	s_nop 1
	v_cndmask_b32_e32 v18, 0, v209, vcc
	v_cmp_gt_u32_e32 vcc, 16, v19
	v_add_u32_e32 v19, 43, v16
	s_nop 0
	v_cndmask_b32_e32 v190, 0, v210, vcc
	v_or_b32_e32 v191, v190, v18
	v_add_u32_e32 v18, 42, v16
	v_cmp_gt_u32_e32 vcc, 16, v18
	s_nop 1
	v_cndmask_b32_e32 v18, 0, v209, vcc
	v_cmp_gt_u32_e32 vcc, 16, v19
	s_nop 1
	v_cndmask_b32_e32 v192, 0, v210, vcc
	v_or_b32_e32 v193, v192, v18
	v_cmp_eq_u32_e32 vcc, s3, v17
	v_add_u32_e32 v18, 49, v16
	v_readlane_b32 s3, v254, 58
	v_cndmask_b32_e32 v17, 0, v209, vcc
	v_cmp_gt_u32_e32 vcc, 16, v18
	v_add_u32_e32 v18, 51, v16
	s_nop 0
	v_cndmask_b32_e32 v213, 0, v210, vcc
	v_or_b32_e32 v215, v213, v17
	v_add_u32_e32 v17, 50, v16
	v_cmp_gt_u32_e32 vcc, 16, v17
	s_nop 1
	v_cndmask_b32_e32 v17, 0, v209, vcc
	v_cmp_gt_u32_e32 vcc, 16, v18
	v_add_u32_e32 v18, 57, v16
	s_nop 0
	v_cndmask_b32_e32 v216, 0, v210, vcc
	v_or_b32_e32 v217, v216, v17
	v_add_u32_e32 v17, 56, v16
	v_cmp_gt_u32_e32 vcc, 16, v17
	s_nop 1
	v_cndmask_b32_e32 v17, 0, v209, vcc
	v_cmp_gt_u32_e32 vcc, 16, v18
	s_nop 1
	v_cndmask_b32_e32 v218, 0, v210, vcc
	v_or_b32_e32 v219, v218, v17
	v_add_u32_e32 v17, 58, v16
	v_cmp_gt_u32_e32 vcc, 16, v17
	v_add_u32_e32 v16, 59, v16
	s_nop 0
	v_cndmask_b32_e32 v17, 0, v209, vcc
	v_cmp_gt_u32_e32 vcc, 16, v16
	v_lshlrev_b32_e32 v16, 2, v81
	v_sub_u32_e32 v16, v214, v16
	v_cndmask_b32_e32 v220, 0, v210, vcc
	v_or_b32_e32 v221, v220, v17
	v_add_u32_e32 v214, s3, v16
	s_mov_b32 s3, s42
.LBB0_537:
	s_and_b32 s8, s3, 0x7f
	v_med3_u32 v16, s8, 4, v211
	s_ashr_i32 s9, s3, 10
	v_readfirstlane_b32 s10, v16
	s_lshl_b32 s17, s10, 6
	s_lshl_b32 s10, s9, 13
	s_lshl_b32 s8, s8, 6
	s_or_b32 s8, s10, s8
	s_bfe_u32 s16, s3, 0x30007
	v_or_b32_e32 v16, s8, v81
	s_mul_i32 s18, s9, 10
	v_ashrrev_i32_e32 v17, 31, v16
	s_add_i32 s12, s18, s16
	v_lshlrev_b64 v[18:19], 11, v[16:17]
	s_ashr_i32 s13, s12, 31
	s_lshr_b32 s11, s3, 7
	v_lshl_add_u64 v[18:19], s[66:67], 0, v[18:19]
	s_lshl_b32 s8, s16, 6
	s_lshl_b32 s24, s16, 7
	s_lshl_b64 s[14:15], s[12:13], 15
	v_lshl_add_u64 v[18:19], v[18:19], 0, s[24:25]
	v_mov_b32_e32 v157, v80
	s_add_u32 s14, s76, s14
	v_lshl_add_u64 v[18:19], v[18:19], 0, v[156:157]
	s_addc_u32 s15, s77, s15
	v_mov_b32_e32 v159, v80
	global_load_dwordx4 v[82:85], v[18:19], off offset:32
	global_load_dwordx4 v[86:89], v[18:19], off offset:64
	v_lshl_add_u64 v[20:21], s[14:15], 0, v[158:159]
	global_load_dwordx4 v[126:129], v158, s[14:15]
	global_load_dwordx4 v[114:117], v158, s[14:15] offset:1024
	global_load_dwordx4 v[110:113], v158, s[14:15] offset:2048
	global_load_dwordx4 v[98:101], v158, s[14:15] offset:3072
	global_load_dwordx4 v[90:93], v[18:19], off
	global_load_dwordx4 v[118:121], v189, s[14:15]
	v_add_co_u32_e32 v20, vcc, s49, v20
	s_lshl_b64 s[12:13], s[12:13], 20
	s_nop 0
	v_addc_co_u32_e32 v21, vcc, 0, v21, vcc
	global_load_dwordx4 v[94:97], v[18:19], off offset:96
	global_load_dwordx4 v[122:125], v[20:21], off offset:1024
	global_load_dwordx4 v[106:109], v[20:21], off offset:2048
	global_load_dwordx4 v[102:105], v[20:21], off offset:3072
	s_add_u32 s9, s78, s12
	s_addc_u32 s10, s79, s13
	s_add_i32 s24, s17, 0xffffff00
	s_lshr_b32 s100, s24, 6
	s_sub_u32 s100, 0, s100
	s_and_b32 s100, s100, 7
	s_lshl_b32 s100, s100, 6
	s_add_i32 s24, s24, s100
	s_lshl_b64 s[12:13], s[24:25], 7
	s_add_u32 s12, s9, s12
	s_addc_u32 s13, s10, s13
	s_ashr_i32 s14, s18, 31
	s_add_u32 s22, s18, s16
	s_addc_u32 s23, s14, 0
	s_lshl_b64 s[16:17], s[22:23], 15
	s_add_u32 s14, s58, s16
	v_mov_b32_e32 v143, 0
	v_lshlrev_b64 v[144:145], 10, v[16:17]
	s_addc_u32 s15, s59, s17
	v_lshl_add_u64 v[146:147], v[154:155], 0, s[16:17]
	s_mov_b64 s[26:27], 0
	v_mov_b32_e32 v32, 0
	v_mov_b32_e32 v33, v143
	v_mov_b32_e32 v34, v143
	v_mov_b32_e32 v35, v143
	v_mov_b32_e32 v36, v143
	v_mov_b32_e32 v37, v143
	v_mov_b32_e32 v38, v143
	v_mov_b32_e32 v39, v143
	v_mov_b32_e32 v40, v143
	v_mov_b32_e32 v41, v143
	v_mov_b32_e32 v42, v143
	v_mov_b32_e32 v43, v143
	v_mov_b32_e32 v44, v143
	v_mov_b32_e32 v45, v143
	v_mov_b32_e32 v46, v143
	v_mov_b32_e32 v47, v143
	v_mov_b32_e32 v16, 0
	v_mov_b32_e32 v17, v143
	v_mov_b32_e32 v18, v143
	v_mov_b32_e32 v19, v143
	v_mov_b32_e32 v20, v143
	v_mov_b32_e32 v21, v143
	v_mov_b32_e32 v22, v143
	v_mov_b32_e32 v23, v143
	v_mov_b32_e32 v24, v143
	v_mov_b32_e32 v25, v143
	v_mov_b32_e32 v26, v143
	v_mov_b32_e32 v27, v143
	v_mov_b32_e32 v28, v143
	v_mov_b32_e32 v29, v143
	v_mov_b32_e32 v30, v143
	v_mov_b32_e32 v31, v143
; #define ATT_KS_LIVE(ks) (ATT_LIVE((ks) >> 1, 8 * ((ks) & 1)) || ATT_LIVE((ks) >> 1, 8 * ((ks) & 1) + 4))
; template <int MASK, int QH> ...
;     ...
;         for (int ks = 0; ks < 4; ++ks) if (ATT_KS_LIVE(ks)) vfr[db][ks] = *(const bf16x8*)(vt + ((db * 4 + ks) * 64 + lane) * 8);
;     f32x16 st[2];
; #pragma unroll
;     for (int kb = 0; kb < 2; ++kb) {
; #pragma unroll
;         for (int i = 0; i < 16; ++i) st[kb][i] = negB;
; #pragma unroll
;         for (int kk = 0; kk < 4; ++kk) st[kb] = __builtin_amdgcn_mfma_f32_32x32x16_bf16(kf[kb][kk], qf[kk], st[kb], 0, 0, 0);
;     }
; #pragma unroll
;     for (int kb = 0; kb < 2; ++kb)
; #pragma unroll
;         for (int kk = 0; kk < 4; ++kk) kf[kb][kk] = *(const bf16x8*)(knext + ((kb * 4 + kk) * 64 + lane) * 8);
;     float ls = 0.f;
;     bf16x8 pf[4];
; #pragma unroll
;     for (int kb = 0; kb < 2; ++kb)
; #pragma unroll
;         for (int hs = 0; hs < 2; ++hs) {
;             if (!ATT_KS_LIVE(2 * kb + hs)) continue;
;             float pv[8];
; #pragma unroll
;             for (int j = 0; j < 8; ++j) {
;                 const int i = 8 * hs + j, kc = 32 * kb + 8 * (i >> 2) + (i & 3);
;                 if (!ATT_LIVE(kb, i)) { pv[j] = 0.f; continue; }
;                 float s = st[kb][i];
;                 if (MASK == 1) s += tab[mp1 + kc];
;                 float pe = __builtin_amdgcn_exp2f(s);
;                 if (MASK == 2) pe = ((unsigned)(kc + mp0) <= 256u) ? pe : 0.f;
;                 pv[j] = pe; if (MASK != 1) ls += pe;
;             }
;             v4u w; w.x = pk2(pv[0], pv[1]); w.y = pk2(pv[2], pv[3]); w.z = pk2(pv[4], pv[5]); w.w = pk2(pv[6], pv[7]);
;             if (MASK == 1) {
;                 unsigned wm[4] = {w.x, w.y, w.z, w.w};
; #pragma unroll
;                 for (int t = 0; t < 4; ++t) { if (!ATT_LIVE(kb, 8 * hs + 2 * t)) { wm[t] = 0u; continue; }
;                     wm[t] &= mw[kb][4 * hs + t];
;                     ls += __uint_as_float(wm[t] << 16); ls += __uint_as_float(wm[t] & 0xffff0000u); }
;                 w.x = wm[0]; w.y = wm[1]; w.z = wm[2]; w.w = wm[3];
;             }
;             pf[2 * kb + hs] = __builtin_bit_cast(bf16x8, w);
;         }
;     l += ls;
; #pragma unroll
;     for (int db = 0; db < 2; ++db)
; #pragma unroll
;         for (int ks = 0; ks < 4; ++ks) if (ATT_KS_LIVE(ks)) ot[db] = __builtin_amdgcn_mfma_f32_32x32x16_bf16(vfr[db][ks], pf[ks], ot[db], 0, 0, 0);
.LBB0_538:
	s_waitcnt vmcnt(5)
	v_mfma_f32_32x32x16_bf16 v[64:79], v[126:129], v[90:93], v[0:15]
	v_lshl_add_u64 v[126:127], v[146:147], 0, s[26:27]
	s_add_u32 s16, s14, s26
	s_addc_u32 s17, s15, s27
	s_add_u32 s16, s16, 0x15202000
	s_addc_u32 s17, s17, 0
	s_cmpk_eq_i32 s26, 0x6000
	s_cselect_b32 s29, s13, s17
	s_waitcnt vmcnt(4)
	v_mfma_f32_32x32x16_bf16 v[48:63], v[118:121], v[90:93], v[0:15]
	v_add_co_u32_e32 v118, vcc, s47, v126
	s_cselect_b32 s28, s12, s16
	s_nop 0
	v_addc_co_u32_e32 v119, vcc, 0, v127, vcc
	v_add_co_u32_e32 v120, vcc, s4, v126
	v_mfma_f32_32x32x16_bf16 v[64:79], v[114:117], v[82:85], v[64:79]
	s_nop 0
	v_addc_co_u32_e32 v121, vcc, 0, v127, vcc
	global_load_dwordx4 v[222:225], v[120:121], off offset:-4096
	global_load_dwordx4 v[226:229], v[120:121], off
	global_load_dwordx4 v[230:233], v[118:119], off offset:1024
	global_load_dwordx4 v[134:137], v[118:119], off offset:2048
	global_load_dwordx4 v[234:237], v[120:121], off offset:1024
	global_load_dwordx4 v[138:141], v[118:119], off offset:3072
	global_load_dwordx4 v[238:241], v[120:121], off offset:2048
	global_load_dwordx4 v[130:133], v[120:121], off offset:3072
	s_waitcnt vmcnt(10)
	v_mfma_f32_32x32x16_bf16 v[48:63], v[122:125], v[82:85], v[48:63]
	global_load_dwordx4 v[126:129], v158, s[28:29]
	global_load_dwordx4 v[118:121], v189, s[28:29]
	s_add_u32 s26, s26, 0x2000
	s_addc_u32 s27, s27, 0
	s_cmpk_eq_u32 s26, 0x8000
	v_mfma_f32_32x32x16_bf16 v[64:79], v[110:113], v[86:89], v[64:79]
	s_waitcnt vmcnt(11)
	v_mfma_f32_32x32x16_bf16 v[48:63], v[106:109], v[86:89], v[48:63]
	v_mfma_f32_32x32x16_bf16 v[64:79], v[98:101], v[94:97], v[64:79]
	global_load_dwordx4 v[114:117], v158, s[28:29] offset:1024
	global_load_dwordx4 v[122:125], v194, s[28:29]
	global_load_dwordx4 v[106:109], v195, s[28:29]
	global_load_dwordx4 v[110:113], v158, s[28:29] offset:2048
	global_load_dwordx4 v[98:101], v158, s[28:29] offset:3072
	s_nop 6
	v_exp_f32_e32 v64, v64
	s_waitcnt vmcnt(15)
	v_mfma_f32_32x32x16_bf16 v[48:63], v[102:105], v[94:97], v[48:63]
	global_load_dwordx4 v[102:105], v212, s[28:29]
	v_exp_f32_e32 v65, v65
	v_exp_f32_e32 v66, v66
	v_exp_f32_e32 v67, v67
	v_exp_f32_e32 v68, v68
	v_exp_f32_e32 v69, v69
	v_exp_f32_e32 v70, v70
	v_exp_f32_e32 v71, v71
	s_nop 3
	v_exp_f32_e32 v157, v48
	v_exp_f32_e32 v159, v49
	v_exp_f32_e32 v242, v50
	v_exp_f32_e32 v243, v51
	v_cvt_pk_bf16_f32 v48, v64, v65
	v_cvt_pk_bf16_f32 v49, v66, v67
	v_cvt_pk_bf16_f32 v50, v68, v69
	v_cvt_pk_bf16_f32 v51, v70, v71
	v_exp_f32_e32 v72, v72
	v_exp_f32_e32 v73, v73
	v_exp_f32_e32 v74, v74
	v_exp_f32_e32 v75, v75
	v_exp_f32_e32 v76, v76
	v_exp_f32_e32 v77, v77
	v_exp_f32_e32 v78, v78
	v_exp_f32_e32 v79, v79
	v_add_f32_e32 v64, 0, v64
	v_exp_f32_e32 v244, v52
	s_waitcnt vmcnt(15)
	v_mfma_f32_32x32x16_bf16 v[32:47], v[222:225], v[48:51], v[32:47]
	v_exp_f32_e32 v222, v53
	v_exp_f32_e32 v223, v54
	v_exp_f32_e32 v224, v55
	v_cvt_pk_bf16_f32 v52, v157, v159
	v_cvt_pk_bf16_f32 v53, v242, v243
	v_cvt_pk_bf16_f32 v54, v244, v222
	v_cvt_pk_bf16_f32 v55, v223, v224
	s_waitcnt vmcnt(14)
	v_mfma_f32_32x32x16_bf16 v[16:31], v[226:229], v[48:51], v[16:31]
	v_cvt_pk_bf16_f32 v48, v72, v73
	v_cvt_pk_bf16_f32 v49, v74, v75
	v_cvt_pk_bf16_f32 v50, v76, v77
	v_cvt_pk_bf16_f32 v51, v78, v79
	v_exp_f32_e32 v225, v56
	v_exp_f32_e32 v245, v57
	v_exp_f32_e32 v246, v58
	s_waitcnt vmcnt(13)
	v_mfma_f32_32x32x16_bf16 v[32:47], v[230:233], v[48:51], v[32:47]
	v_exp_f32_e32 v247, v59
	v_exp_f32_e32 v60, v60
	v_exp_f32_e32 v61, v61
	v_exp_f32_e32 v62, v62
	v_exp_f32_e32 v63, v63
	v_cvt_pk_bf16_f32 v56, v225, v245
	v_cvt_pk_bf16_f32 v57, v246, v247
	s_waitcnt vmcnt(11)
	v_mfma_f32_32x32x16_bf16 v[16:31], v[234:237], v[48:51], v[16:31]
	v_add_f32_e32 v48, v65, v64
	v_add_f32_e32 v48, v66, v48
	v_add_f32_e32 v48, v67, v48
	v_add_f32_e32 v48, v68, v48
	v_add_f32_e32 v48, v69, v48
	v_add_f32_e32 v48, v70, v48
	v_add_f32_e32 v48, v71, v48
	v_add_f32_e32 v48, v72, v48
	v_add_f32_e32 v48, v73, v48
	v_add_f32_e32 v48, v74, v48
	v_add_f32_e32 v48, v75, v48
	v_add_f32_e32 v48, v76, v48
	v_add_f32_e32 v48, v77, v48
	v_add_f32_e32 v48, v78, v48
	v_add_f32_e32 v48, v79, v48
	v_add_f32_e32 v48, v157, v48
	v_mfma_f32_32x32x16_bf16 v[32:47], v[134:137], v[52:55], v[32:47]
	v_add_f32_e32 v48, v159, v48
	v_add_f32_e32 v48, v242, v48
	v_add_f32_e32 v48, v243, v48
	v_add_f32_e32 v48, v244, v48
	v_add_f32_e32 v48, v222, v48
	v_add_f32_e32 v48, v223, v48
	v_add_f32_e32 v48, v224, v48
	s_waitcnt vmcnt(9)
	v_mfma_f32_32x32x16_bf16 v[16:31], v[238:241], v[52:55], v[16:31]
	v_cvt_pk_bf16_f32 v58, v60, v61
	v_cvt_pk_bf16_f32 v59, v62, v63
	v_add_f32_e32 v48, v225, v48
	v_add_f32_e32 v48, v245, v48
	v_add_f32_e32 v48, v246, v48
	v_add_f32_e32 v48, v247, v48
	v_add_f32_e32 v48, v60, v48
	v_mfma_f32_32x32x16_bf16 v[32:47], v[138:141], v[56:59], v[32:47]
	v_add_f32_e32 v48, v61, v48
	v_add_f32_e32 v48, v62, v48
	v_add_f32_e32 v48, v63, v48
	v_add_f32_e32 v143, v143, v48
	s_waitcnt vmcnt(8)
	v_mfma_f32_32x32x16_bf16 v[16:31], v[130:133], v[56:59], v[16:31]
	s_cbranch_scc0 .LBB0_538
	s_and_b32 s12, s2, 0x7f
	s_and_b32 s11, s11, 7
	v_med3_u32 v49, s12, 4, v211
	s_movk_i32 s13, 0x7c
	s_mulk_i32 s11, 0xa00
	v_mul_lo_u32 v48, v49, s13
	v_add_u32_e32 v48, s11, v48
	s_mulk_i32 s12, 0x7c
	v_subrev_u32_e32 v48, s12, v48
	v_add_u32_e32 v157, v214, v48
	v_mov_b32_e32 v48, s2
	s_nop 0
	v_readfirstlane_b32 s11, v48
	s_and_b32 s24, s11, 0x7f
	v_cmp_gt_u64_e64 s[12:13], s[24:25], 4
	s_and_b64 s[12:13], s[12:13], exec
	s_cselect_b32 s24, s24, 4
	v_cmp_lt_u64_e32 vcc, s[24:25], v[170:171]
	s_and_b64 s[12:13], vcc, exec
	s_cselect_b32 s11, s24, 0x7c
	s_lshl_b32 s11, s11, 13
	v_readfirstlane_b32 s12, v49
	s_lshl_b64 s[14:15], s[22:23], 20
	s_lshl_b32 s12, s12, 6
	s_or_b32 s14, s14, s11
	s_addk_i32 s12, 0xff00
	v_lshl_add_u64 v[146:147], v[154:155], 0, s[14:15]
	s_lshr_b32 s100, s12, 6
	s_sub_u32 s100, 0, s100
	s_and_b32 s100, s100, 7
	s_lshl_b32 s22, s100, 13
	s_mov_b32 s23, 0
	s_lshl_b32 s101, s100, 6
	s_add_i32 s12, s12, s101
	s_mulk_i32 s100, 0x7c
	v_add_u32_e32 v157, s100, v157
	s_mov_b32 s100, s22
; #define ATT_KS_LIVE(ks) (ATT_LIVE((ks) >> 1, 8 * ((ks) & 1)) || ATT_LIVE((ks) >> 1, 8 * ((ks) & 1) + 4))
; template <int MASK, int QH> ...
;     ...
;         for (int ks = 0; ks < 4; ++ks) if (ATT_KS_LIVE(ks)) vfr[db][ks] = *(const bf16x8*)(vt + ((db * 4 + ks) * 64 + lane) * 8);
;     f32x16 st[2];
; #pragma unroll
;     for (int kb = 0; kb < 2; ++kb) {
; #pragma unroll
;         for (int i = 0; i < 16; ++i) st[kb][i] = negB;
; #pragma unroll
;         for (int kk = 0; kk < 4; ++kk) st[kb] = __builtin_amdgcn_mfma_f32_32x32x16_bf16(kf[kb][kk], qf[kk], st[kb], 0, 0, 0);
;     }
; #pragma unroll
;     for (int kb = 0; kb < 2; ++kb)
; #pragma unroll
;         for (int kk = 0; kk < 4; ++kk) kf[kb][kk] = *(const bf16x8*)(knext + ((kb * 4 + kk) * 64 + lane) * 8);
;     float ls = 0.f;
;     bf16x8 pf[4];
; #pragma unroll
;     for (int kb = 0; kb < 2; ++kb)
; #pragma unroll
;         for (int hs = 0; hs < 2; ++hs) {
;             if (!ATT_KS_LIVE(2 * kb + hs)) continue;
;             float pv[8];
; #pragma unroll
;             for (int j = 0; j < 8; ++j) {
;                 const int i = 8 * hs + j, kc = 32 * kb + 8 * (i >> 2) + (i & 3);
;                 if (!ATT_LIVE(kb, i)) { pv[j] = 0.f; continue; }
;                 float s = st[kb][i];
;                 if (MASK == 1) s += tab[mp1 + kc];
;                 float pe = __builtin_amdgcn_exp2f(s);
;                 if (MASK == 2) pe = ((unsigned)(kc + mp0) <= 256u) ? pe : 0.f;
;                 pv[j] = pe; if (MASK != 1) ls += pe;
;             }
;             v4u w; w.x = pk2(pv[0], pv[1]); w.y = pk2(pv[2], pv[3]); w.z = pk2(pv[4], pv[5]); w.w = pk2(pv[6], pv[7]);
;             if (MASK == 1) {
;                 unsigned wm[4] = {w.x, w.y, w.z, w.w};
; #pragma unroll
;                 for (int t = 0; t < 4; ++t) { if (!ATT_LIVE(kb, 8 * hs + 2 * t)) { wm[t] = 0u; continue; }
;                     wm[t] &= mw[kb][4 * hs + t];
;                     ls += __uint_as_float(wm[t] << 16); ls += __uint_as_float(wm[t] & 0xffff0000u); }
;                 w.x = wm[0]; w.y = wm[1]; w.z = wm[2]; w.w = wm[3];
;             }
;             pf[2 * kb + hs] = __builtin_bit_cast(bf16x8, w);
;         }
;     l += ls;
; #pragma unroll
;     for (int db = 0; db < 2; ++db)
; #pragma unroll
;         for (int ks = 0; ks < 4; ++ks) if (ATT_KS_LIVE(ks)) ot[db] = __builtin_amdgcn_mfma_f32_32x32x16_bf16(vfr[db][ks], pf[ks], ot[db], 0, 0, 0);
.LBB0_540:
	s_waitcnt vmcnt(7)
	v_mfma_f32_32x32x16_bf16 v[52:67], v[126:129], v[90:93], v[0:15]
	v_lshl_add_u64 v[48:49], v[146:147], 0, s[22:23]
	v_add_co_u32_e32 v50, vcc, s5, v48
	s_nop 0
	v_addc_co_u32_e32 v51, vcc, 0, v49, vcc
	v_add_co_u32_e32 v48, vcc, s6, v48
	s_waitcnt vmcnt(5)
	v_mfma_f32_32x32x16_bf16 v[52:67], v[114:117], v[82:85], v[52:67]
	v_addc_co_u32_e32 v49, vcc, 0, v49, vcc
	global_load_dwordx4 v[68:71], v[50:51], off offset:1024
	global_load_dwordx4 v[72:75], v[50:51], off offset:2048
	global_load_dwordx4 v[76:79], v[50:51], off offset:3072
	global_load_dwordx4 v[130:133], v[48:49], off offset:1024
	global_load_dwordx4 v[134:137], v[48:49], off offset:2048
	global_load_dwordx4 v[138:141], v[48:49], off offset:3072
	s_add_u32 s22, s22, 0x2000
	s_and_b32 s22, s22, 0xffff
	s_cmp_eq_u32 s22, 0
	s_cselect_b32 s11, 0xfffffe40, 64
	s_cselect_b32 s101, 0x3e0, 0
	s_add_i32 s11, s12, s11
	s_mov_b32 s12, s11
	s_ashr_i32 s13, s12, 31
	s_waitcnt vmcnt(8)
	v_mfma_f32_32x32x16_bf16 v[52:67], v[110:113], v[86:89], v[52:67]
	s_lshl_b64 s[12:13], s[12:13], 7
	s_add_u32 s26, s9, s12
	s_addc_u32 s27, s10, s13
	v_mov_b32_e32 v159, v80
	s_cmp_lg_u32 s22, s100
	s_waitcnt vmcnt(7)
	v_mfma_f32_32x32x16_bf16 v[52:67], v[98:101], v[94:97], v[52:67]
	global_load_dwordx4 v[126:129], v158, s[26:27]
	global_load_dwordx4 v[114:117], v158, s[26:27] offset:1024
	global_load_dwordx4 v[110:113], v158, s[26:27] offset:2048
	global_load_dwordx4 v[98:101], v158, s[26:27] offset:3072
	s_mov_b32 s12, s11
	v_mfma_f32_32x32x16_bf16 v[48:63], v[118:121], v[90:93], v[0:15]
	v_mfma_f32_32x32x16_bf16 v[48:63], v[122:125], v[82:85], v[48:63]
	v_mfma_f32_32x32x16_bf16 v[48:63], v[106:109], v[86:89], v[48:63]
	s_waitcnt vmcnt(10)
	v_mfma_f32_32x32x16_bf16 v[48:63], v[102:105], v[94:97], v[48:63]
	v_lshl_add_u64 v[102:103], s[26:27], 0, v[158:159]
	v_add_co_u32_e32 v102, vcc, s49, v102
	s_nop 1
	v_addc_co_u32_e32 v103, vcc, 0, v103, vcc
	global_load_dwordx4 v[118:121], v[102:103], off
	global_load_dwordx4 v[122:125], v[102:103], off offset:1024
	global_load_dwordx4 v[106:109], v[102:103], off offset:2048
	s_nop 0
	global_load_dwordx4 v[102:105], v212, s[26:27]
	ds_read2_b32 v[222:223], v157 offset1:1
	s_waitcnt lgkmcnt(0)
	v_add_f32_e32 v64, v64, v222
	v_exp_f32_e32 v159, v64
	v_add_f32_e32 v64, v65, v223
	v_exp_f32_e32 v222, v64
	ds_read2_b32 v[64:65], v157 offset0:2 offset1:3
	s_waitcnt lgkmcnt(0)
	v_add_f32_e32 v64, v66, v64
	v_add_f32_e32 v65, v67, v65
	v_exp_f32_e32 v64, v64
	v_exp_f32_e32 v65, v65
	v_cvt_pk_bf16_f32 v67, v159, v222
	v_and_b32_e32 v66, v149, v67
	v_cvt_pk_bf16_f32 v159, v64, v65
	v_lshlrev_b32_e32 v64, 16, v66
	v_add_f32_e32 v64, 0, v64
	v_and_b32_e32 v65, v148, v67
	v_and_b32_e32 v67, v151, v159
	v_add_f32_e32 v222, v64, v65
	v_lshlrev_b32_e32 v223, 16, v67
	v_add_f32_e32 v222, v222, v223
	v_and_b32_e32 v159, v150, v159
	v_add_f32_e32 v159, v222, v159
	ds_read2_b32 v[222:223], v157 offset0:8 offset1:9
	v_mov_b32_e32 v64, v80
	v_mov_b32_e32 v65, v80
	s_waitcnt lgkmcnt(0)
	v_add_f32_e32 v48, v48, v222
	v_exp_f32_e32 v222, v48
	v_add_f32_e32 v48, v49, v223
	v_exp_f32_e32 v223, v48
	ds_read2_b32 v[48:49], v157 offset0:10 offset1:11
	s_waitcnt vmcnt(13)
	v_mfma_f32_32x32x16_bf16 v[32:47], v[68:71], v[64:67], v[32:47]
	s_waitcnt lgkmcnt(0)
	v_add_f32_e32 v48, v50, v48
	v_exp_f32_e32 v50, v48
	v_add_f32_e32 v48, v51, v49
	v_exp_f32_e32 v51, v48
	ds_read2_b32 v[48:49], v157 offset0:16 offset1:17
	s_waitcnt vmcnt(10)
	v_mfma_f32_32x32x16_bf16 v[16:31], v[130:133], v[64:67], v[16:31]
	v_cvt_pk_bf16_f32 v50, v50, v51
	s_waitcnt lgkmcnt(0)
	v_add_f32_e32 v48, v52, v48
	v_exp_f32_e32 v52, v48
	v_add_f32_e32 v48, v53, v49
	v_exp_f32_e32 v53, v48
	ds_read2_b32 v[48:49], v157 offset0:18 offset1:19
	v_cvt_pk_bf16_f32 v51, v52, v53
	s_waitcnt lgkmcnt(0)
	v_add_f32_e32 v48, v54, v48
	v_add_f32_e32 v49, v55, v49
	v_exp_f32_e32 v48, v48
	v_exp_f32_e32 v49, v49
	v_cvt_pk_bf16_f32 v54, v222, v223
	v_and_b32_e32 v53, v152, v54
	v_cvt_pk_bf16_f32 v52, v48, v49
	v_and_b32_e32 v48, v153, v54
	v_lshlrev_b32_e32 v49, 16, v48
	v_add_f32_e32 v49, v159, v49
	v_add_f32_e32 v53, v49, v53
	v_and_b32_e32 v49, v161, v50
	v_lshlrev_b32_e32 v54, 16, v49
	v_add_f32_e32 v53, v53, v54
	v_and_b32_e32 v50, v160, v50
	v_add_f32_e32 v53, v53, v50
	v_and_b32_e32 v50, v191, v51
	v_lshlrev_b32_e32 v54, 16, v50
	v_add_f32_e32 v53, v53, v54
	v_and_b32_e32 v51, v190, v51
	v_add_f32_e32 v53, v53, v51
	v_and_b32_e32 v51, v193, v52
	v_lshlrev_b32_e32 v54, 16, v51
	v_add_f32_e32 v53, v53, v54
	v_and_b32_e32 v52, v192, v52
	v_add_f32_e32 v54, v53, v52
	ds_read2_b32 v[52:53], v157 offset0:24 offset1:25
	v_mfma_f32_32x32x16_bf16 v[32:47], v[72:75], v[48:51], v[32:47]
	s_waitcnt lgkmcnt(0)
	v_add_f32_e32 v52, v56, v52
	v_exp_f32_e32 v55, v52
	v_add_f32_e32 v52, v57, v53
	v_exp_f32_e32 v56, v52
	ds_read2_b32 v[52:53], v157 offset0:26 offset1:27
	s_waitcnt vmcnt(9)
	v_mfma_f32_32x32x16_bf16 v[16:31], v[134:137], v[48:51], v[16:31]
	v_cvt_pk_bf16_f32 v55, v55, v56
	s_waitcnt lgkmcnt(0)
	v_add_f32_e32 v52, v58, v52
	v_exp_f32_e32 v57, v52
	v_add_f32_e32 v52, v59, v53
	v_exp_f32_e32 v58, v52
	ds_read2_b32 v[52:53], v157 offset0:32 offset1:33
	v_cvt_pk_bf16_f32 v56, v57, v58
	s_waitcnt lgkmcnt(0)
	v_add_f32_e32 v52, v60, v52
	v_exp_f32_e32 v59, v52
	v_add_f32_e32 v52, v61, v53
	v_exp_f32_e32 v60, v52
	ds_read2_b32 v[52:53], v157 offset0:34 offset1:35
	v_add_u32_e32 v157, 0x7c, v157
	v_subrev_u32_e32 v157, s101, v157
	v_cvt_pk_bf16_f32 v57, v59, v60
	s_waitcnt lgkmcnt(0)
	v_add_f32_e32 v52, v62, v52
	v_add_f32_e32 v53, v63, v53
	v_exp_f32_e32 v52, v52
	v_exp_f32_e32 v53, v53
	s_nop 0
	v_cvt_pk_bf16_f32 v58, v52, v53
	v_and_b32_e32 v52, v215, v55
	v_lshlrev_b32_e32 v53, 16, v52
	v_add_f32_e32 v53, v54, v53
	v_and_b32_e32 v54, v213, v55
	v_add_f32_e32 v54, v53, v54
	v_and_b32_e32 v53, v217, v56
	v_lshlrev_b32_e32 v55, 16, v53
	v_add_f32_e32 v54, v54, v55
	v_and_b32_e32 v55, v216, v56
	v_add_f32_e32 v55, v54, v55
	v_and_b32_e32 v54, v219, v57
	v_lshlrev_b32_e32 v56, 16, v54
	v_add_f32_e32 v55, v55, v56
	v_and_b32_e32 v56, v218, v57
	v_add_f32_e32 v56, v55, v56
	v_and_b32_e32 v55, v221, v58
	v_lshlrev_b32_e32 v57, 16, v55
	v_add_f32_e32 v56, v56, v57
	v_mfma_f32_32x32x16_bf16 v[32:47], v[76:79], v[52:55], v[32:47]
	v_and_b32_e32 v57, v220, v58
	v_add_f32_e32 v56, v56, v57
	v_add_f32_e32 v143, v143, v56
	s_waitcnt vmcnt(8)
	v_mfma_f32_32x32x16_bf16 v[16:31], v[138:141], v[52:55], v[16:31]
	s_cbranch_scc1 .LBB0_540
; __device__ __forceinline__ unsigned pk2(float lo, float hi) { return __builtin_bit_cast(unsigned, __builtin_convertvector((f32x2_t){lo, hi}, bf16x2_t)); }
; template <int KIND, int QH>
; __device__ __forceinline__ void attn_unit(const AttnBufs& a, int u, int lane, const LAS float* rpbt, float bndA, float bndB) {
;     ...
;     l += __shfl_xor(l, 32);
;     const float inv = 1.0f / l;
;     bf16* op = a.O + (size_t)(qrow0 + r32) * DM + head16 * 64 + 4 * half;
; #pragma unroll
;     for (int db = 0; db < 2; ++db)
; #pragma unroll
;         for (int g = 0; g < 4; ++g) { v2u w; w.x = pk2(ot[db][4 * g] * inv, ot[db][4 * g + 1] * inv); w.y = pk2(ot[db][4 * g + 2] * inv, ot[db][4 * g + 3] * inv);
;             *(v2u*)(op + 32 * db + 8 * g) = w; }
; __device__ __forceinline__ void attn_phase(const AttnBufs& a, const float* rpb_l, const float* qkg, bool with_ctx, LAS unsigned char* lds) {
;     ...
;     for (int u = gw; u < 4096; u += NGW) attn_unit<0, 0>(a, u, lane, tab, bndA, bndB);
	ds_bpermute_b32 v50, v175, v143
	s_lshl_b32 s24, s8, 1
	v_lshl_add_u64 v[48:49], v[144:145], 1, s[68:69]
	v_lshl_add_u64 v[48:49], v[48:49], 0, s[24:25]
	s_add_i32 s3, s3, s84
	s_waitcnt lgkmcnt(0)
	v_add_f32_e32 v50, v143, v50
	v_div_scale_f32 v51, s[8:9], v50, v50, 1.0
	v_rcp_f32_e32 v52, v51
	v_div_scale_f32 v53, vcc, 1.0, v50, 1.0
	v_mov_b32_e32 v143, v80
	v_fma_f32 v54, -v51, v52, 1.0
	v_fmac_f32_e32 v52, v54, v52
	v_mul_f32_e32 v54, v53, v52
	v_fma_f32 v55, -v51, v54, v53
	v_fmac_f32_e32 v54, v55, v52
	v_fma_f32 v51, -v51, v54, v53
	v_div_fmas_f32 v51, v51, v52, v54
	v_div_fixup_f32 v50, v51, v50, 1.0
	v_pk_mul_f32 v[32:33], v[32:33], v[50:51] op_sel_hi:[1,0]
	v_pk_mul_f32 v[34:35], v[34:35], v[50:51] op_sel_hi:[1,0]
	v_pk_mul_f32 v[16:17], v[16:17], v[50:51] op_sel_hi:[1,0]
	v_pk_mul_f32 v[18:19], v[18:19], v[50:51] op_sel_hi:[1,0]
	v_lshl_add_u64 v[48:49], v[48:49], 0, v[142:143]
	v_cvt_pk_bf16_f32 v32, v32, v33
	v_cvt_pk_bf16_f32 v33, v34, v35
	v_cvt_pk_bf16_f32 v16, v16, v17
	v_cvt_pk_bf16_f32 v17, v18, v19
	global_store_dwordx2 v[48:49], v[32:33], off
	v_pk_mul_f32 v[32:33], v[36:37], v[50:51] op_sel_hi:[1,0]
	v_pk_mul_f32 v[34:35], v[38:39], v[50:51] op_sel_hi:[1,0]
	global_store_dwordx2 v[48:49], v[16:17], off offset:64
	v_pk_mul_f32 v[16:17], v[20:21], v[50:51] op_sel_hi:[1,0]
	v_pk_mul_f32 v[18:19], v[22:23], v[50:51] op_sel_hi:[1,0]
	v_cvt_pk_bf16_f32 v32, v32, v33
	v_cvt_pk_bf16_f32 v33, v34, v35
	v_cvt_pk_bf16_f32 v16, v16, v17
	v_cvt_pk_bf16_f32 v17, v18, v19
	global_store_dwordx2 v[48:49], v[32:33], off offset:16
	v_pk_mul_f32 v[32:33], v[40:41], v[50:51] op_sel_hi:[1,0]
	v_pk_mul_f32 v[34:35], v[42:43], v[50:51] op_sel_hi:[1,0]
	global_store_dwordx2 v[48:49], v[16:17], off offset:80
	v_pk_mul_f32 v[16:17], v[24:25], v[50:51] op_sel_hi:[1,0]
	v_pk_mul_f32 v[18:19], v[26:27], v[50:51] op_sel_hi:[1,0]
	v_cvt_pk_bf16_f32 v32, v32, v33
	v_cvt_pk_bf16_f32 v33, v34, v35
	v_cvt_pk_bf16_f32 v16, v16, v17
	v_cvt_pk_bf16_f32 v17, v18, v19
	global_store_dwordx2 v[48:49], v[32:33], off offset:32
	v_pk_mul_f32 v[32:33], v[44:45], v[50:51] op_sel_hi:[1,0]
	v_pk_mul_f32 v[34:35], v[46:47], v[50:51] op_sel_hi:[1,0]
	global_store_dwordx2 v[48:49], v[16:17], off offset:96
	v_pk_mul_f32 v[16:17], v[28:29], v[50:51] op_sel_hi:[1,0]
	v_pk_mul_f32 v[18:19], v[30:31], v[50:51] op_sel_hi:[1,0]
	s_add_i32 s2, s2, s84
	v_cvt_pk_bf16_f32 v32, v32, v33
	v_cvt_pk_bf16_f32 v33, v34, v35
	v_cvt_pk_bf16_f32 v16, v16, v17
	v_cvt_pk_bf16_f32 v17, v18, v19
	s_cmpk_gt_i32 s3, 0xfff
	global_store_dwordx2 v[48:49], v[32:33], off offset:48
	global_store_dwordx2 v[48:49], v[16:17], off offset:112
	s_cbranch_scc0 .LBB0_537

; __global__ void __launch_bounds__(NWAVES * 64, 2) fwd_mega(Params p) {
	.amdhsa_kernel _Z8fwd_mega6Params
		.amdhsa_group_segment_fixed_size 0
		.amdhsa_private_segment_fixed_size 0
		.amdhsa_kernarg_size 384
		.amdhsa_user_sgpr_count 2
		.amdhsa_user_sgpr_dispatch_ptr 0
		.amdhsa_user_sgpr_queue_ptr 0
		.amdhsa_user_sgpr_kernarg_segment_ptr 1
		.amdhsa_user_sgpr_dispatch_id 0
		.amdhsa_user_sgpr_kernarg_preload_length 0
		.amdhsa_user_sgpr_kernarg_preload_offset 0
		.amdhsa_user_sgpr_private_segment_size 0
		.amdhsa_uses_dynamic_stack 0
		.amdhsa_enable_private_segment 0
		.amdhsa_system_sgpr_workgroup_id_x 1
		.amdhsa_system_sgpr_workgroup_id_y 0
		.amdhsa_system_sgpr_workgroup_id_z 0
		.amdhsa_system_sgpr_workgroup_info 0
		.amdhsa_system_vgpr_workitem_id 2
		.amdhsa_next_free_vgpr 255
		.amdhsa_next_free_sgpr 102
		.amdhsa_accum_offset 256
		.amdhsa_reserve_vcc 1
		.amdhsa_float_round_mode_32 0
		.amdhsa_float_round_mode_16_64 0
		.amdhsa_float_denorm_mode_32 3
		.amdhsa_float_denorm_mode_16_64 3
		.amdhsa_dx10_clamp 1
		.amdhsa_ieee_mode 1
		.amdhsa_fp16_overflow 0
		.amdhsa_tg_split 0
		.amdhsa_exception_fp_ieee_invalid_op 0
		.amdhsa_exception_fp_denorm_src 0
		.amdhsa_exception_fp_ieee_div_zero 0
		.amdhsa_exception_fp_ieee_overflow 0
		.amdhsa_exception_fp_ieee_underflow 0
		.amdhsa_exception_fp_ieee_inexact 0
		.amdhsa_exception_int_div_zero 0
	.end_amdhsa_kernel

; __global__ void __launch_bounds__(NWAVES * 64, 2) fwd_mega(Params p) {
amdhsa.kernels:
  - .agpr_count:     0
    .args:
      - .offset:         0
        .size:           128
        .value_kind:     by_value
      - .offset:         128
        .size:           4
        .value_kind:     hidden_block_count_x
      - .offset:         132
        .size:           4
        .value_kind:     hidden_block_count_y
      - .offset:         136
        .size:           4
        .value_kind:     hidden_block_count_z
      - .offset:         140
        .size:           2
        .value_kind:     hidden_group_size_x
      - .offset:         142
        .size:           2
        .value_kind:     hidden_group_size_y
      - .offset:         144
        .size:           2
        .value_kind:     hidden_group_size_z
      - .offset:         146
        .size:           2
        .value_kind:     hidden_remainder_x
      - .offset:         148
        .size:           2
        .value_kind:     hidden_remainder_y
      - .offset:         150
        .size:           2
        .value_kind:     hidden_remainder_z
      - .offset:         168
        .size:           8
        .value_kind:     hidden_global_offset_x
      - .offset:         176
        .size:           8
        .value_kind:     hidden_global_offset_y
      - .offset:         184
        .size:           8
        .value_kind:     hidden_global_offset_z
      - .offset:         192
        .size:           2
        .value_kind:     hidden_grid_dims
      - .offset:         216
        .size:           8
        .value_kind:     hidden_multigrid_sync_arg
      - .offset:         248
        .size:           4
        .value_kind:     hidden_dynamic_lds_size
    .group_segment_fixed_size: 0
    .kernarg_segment_align: 8
    .kernarg_segment_size: 384
    .language:       OpenCL C
    .language_version:
      - 2
      - 0
    .max_flat_workgroup_size: 512
    .name:           _Z8fwd_mega6Params
    .private_segment_fixed_size: 0
    .sgpr_count:     108
    .sgpr_spill_count: 187
    .symbol:         _Z8fwd_mega6Params.kd
    .uniform_work_group_size: 1
    .uses_dynamic_stack: false
    .vgpr_count:     255
    .vgpr_spill_count: 0
    .wavefront_size: 64
